# P1 column-tile sweep rotated (gate tiles first, q/k/v tiles last so the attention phase finds them in cache); otherwise v17
# speedup vs baseline: 1.0029x; 1.0029x over previous
; #define LAS __attribute__((address_space(3)))
; __device__ __forceinline__ unsigned xb_ld(unsigned* p)              { return __hip_atomic_load(p, __ATOMIC_RELAXED, __HIP_MEMORY_SCOPE_AGENT); }
; __device__ __forceinline__ void xcd_barrier_complete(unsigned* bar, unsigned x, unsigned& nloc, unsigned& nx) {
;     ...
;         sum = 0u; cnt = 0u; mine = 0u;
; #pragma unroll
;         for (unsigned j = 0; j < 16; ++j) { const unsigned c = xb_ld(&bar[XB_XCNT(j)]); sum += c; cnt += (c > 0u) ? 1u : 0u; mine = (j == x) ? c : mine; }
;         if (sum == G) break;
; __global__ void __launch_bounds__(NTHR, 2) fwd_megakernel(Args args) {
;     ...
;     const int tid0 = threadIdx.x, wave = __builtin_amdgcn_readfirstlane(tid0 >> 6);
;     ...
;     const int G = gridDim.x, bid = blockIdx.x, gw = bid * NWAVES + wave, NGW = G * NWAVES;
;     unsigned char* ws = args.ws;
;     float* rn2 = (float*)(ws + WS_RN2);
;     float* logf = (float*)(ws + WS_LOGF); float* cs = (float*)(ws + WS_CS);
;     bf16* Win_t = (bf16*)(ws + WS_WIN); bf16* Wc_t = (bf16*)(ws + WS_WC); bf16* Wa_t = (bf16*)(ws + WS_WA); bf16* Wmix_t = (bf16*)(ws + WS_WMIX);
;     bf16* W1_t = (bf16*)(ws + WS_W1); bf16* W2_t = (bf16*)(ws + WS_W2);
;     bf16* Z = (bf16*)(ws + WS_Z); bf16* XN = (bf16*)(ws + WS_XN); bf16* CONVY = (bf16*)(ws + WS_CONVY); bf16* ATTO = (bf16*)(ws + WS_ATTO);
;     bf16* XG = (bf16*)(ws + WS_Z + 256 * MiB);
;     float* rowss = (float*)(ws + WS_RSS);
;     float* xres = args.out;
;     volatile LAS unsigned* bst = (volatile LAS unsigned*)(L + att::LDS_BYTES + 65536 + 64);
;     if (tid0 < 2) bst[tid0] = 0u;
;     __syncthreads();
;     const XcdBarrier xbar = xcd_barrier_post((unsigned*)(ws + WS_BAR), bst);
.LBB0_5:
	s_or_b64 exec, exec, s[0:1]
	s_lshr_b32 s97, s6, 6
	s_lshl_b32 s0, s2, 3
	s_add_i32 s24, s97, s0
	s_lshl_b32 s80, s70, 3
	s_add_u32 s88, s68, 0x24000000
	s_addc_u32 s89, s69, 0
	s_add_u32 s18, s68, 0x100000
	s_addc_u32 s19, s69, 0
	s_add_u32 s20, s68, 0x180000
	s_addc_u32 s21, s69, 0
	s_add_u32 s26, s68, 0x200000
	s_addc_u32 s27, s69, 0
	s_add_u32 s28, s68, 0x2a00000
	s_addc_u32 s29, s69, 0
	s_add_u32 s30, s68, 0x2e00000
	s_addc_u32 s31, s69, 0
	s_add_u32 s34, s68, 0x3200000
	s_addc_u32 s35, s69, 0
	s_add_u32 s36, s68, 0x3a00000
	s_addc_u32 s37, s69, 0
	s_add_u32 s38, s68, 0x5a00000
	s_addc_u32 s39, s69, 0
	s_add_u32 s4, s68, 0x8000000
	s_addc_u32 s5, s69, 0
	s_add_u32 s6, s68, 0x1c000000
	s_addc_u32 s7, s69, 0
	s_add_u32 s8, s68, 0x20000000
	s_addc_u32 s9, s69, 0
	s_add_u32 s42, s68, 0x22000000
	s_addc_u32 s43, s69, 0
	s_add_u32 s10, s68, 0x18000000
	s_addc_u32 s11, s69, 0
	s_add_u32 s12, s68, 0x20000
	s_addc_u32 s13, s69, 0
	s_cmpk_lt_i32 s2, 0x100
	s_cselect_b64 s[0:1], -1, 0
	v_writelane_b32 v252, s0, 26
	v_lshrrev_b32_e32 v1, 20, v0
	v_lshrrev_b32_e32 v0, 10, v0
	v_writelane_b32 v252, s1, 27
	s_lshl_b32 s0, s97, 14
	s_add_i32 s0, s0, 0
	s_cmpk_lt_i32 s24, 0x7800
	v_writelane_b32 v252, s0, 28
	s_cselect_b64 s[0:1], -1, 0
	v_writelane_b32 v252, s0, 29
	s_ashr_i32 s25, s24, 31
	v_or_b32_e32 v0, v0, v1
	v_writelane_b32 v252, s1, 30
	s_lshl_b64 s[0:1], s[24:25], 13
	v_writelane_b32 v252, s0, 31
	s_cmpk_lt_i32 s24, 0x4000
	s_mul_i32 s71, s71, s70
	v_writelane_b32 v252, s1, 32
	s_cselect_b64 s[0:1], -1, 0
	v_writelane_b32 v252, s0, 33
	s_mul_i32 s71, s71, s16
	v_mbcnt_lo_u32_b32 v1, -1, 0
	v_writelane_b32 v252, s1, 34
	s_add_u32 s0, s68, 0x4200
	s_addc_u32 s1, s69, 0
	v_writelane_b32 v252, s0, 35
	v_mov_b32_e32 v193, 0
	v_mov_b32_e32 v237, 0x358637bd
	v_writelane_b32 v252, s1, 36
	s_add_u32 s0, s68, 0x4400
	s_addc_u32 s1, s69, 0
	v_writelane_b32 v252, s0, 37
	v_mov_b32_e32 v206, 0x260
	v_mbcnt_hi_u32_b32 v203, -1, v1
	v_writelane_b32 v252, s1, 38
	s_add_u32 s0, s68, 0x4500
	s_addc_u32 s1, s69, 0
	v_writelane_b32 v252, s0, 39
	v_mov_b32_e32 v207, 0xff800000
	v_mov_b32_e32 v208, 0x5000
	v_writelane_b32 v252, s1, 40
	s_add_u32 s0, s68, 0x4600
	s_addc_u32 s1, s69, 0
	v_writelane_b32 v252, s0, 41
	v_mov_b64_e32 v[232:233], 0x200
	v_mov_b64_e32 v[204:205], 0x1ff
	v_writelane_b32 v252, s1, 42
	s_add_u32 s0, s68, 0x4700
	s_addc_u32 s1, s69, 0
	v_writelane_b32 v252, s0, 43
	v_mov_b64_e32 v[250:251], 0x7ff
	s_movk_i32 s61, 0x4000
	v_writelane_b32 v252, s1, 44
	s_add_u32 s0, s68, 0x4800
	s_addc_u32 s1, s69, 0
	v_writelane_b32 v252, s0, 45
	s_movk_i32 s81, 0x7fff
	s_mov_b32 s96, 0xffff0000
	v_writelane_b32 v252, s1, 46
	s_add_u32 s0, s68, 0x4900
	s_addc_u32 s1, s69, 0
	v_writelane_b32 v252, s0, 47
	s_movk_i32 s84, 0x1000
	s_movk_i32 s85, 0x5000
	v_writelane_b32 v252, s1, 48
	s_add_u32 s0, s68, 0x4a00
	s_addc_u32 s1, s69, 0
	v_writelane_b32 v252, s0, 49
	s_mov_b32 s90, 0x42000000
	s_mov_b32 s60, 0x3e0293ee
	v_writelane_b32 v252, s1, 50
	s_add_u32 s0, s68, 0x4b00
	s_addc_u32 s1, s69, 0
	v_writelane_b32 v252, s0, 51
	s_nop 1
	v_writelane_b32 v252, s1, 52
	s_add_u32 s0, s68, 0x4c00
	s_addc_u32 s1, s69, 0
	v_writelane_b32 v252, s0, 53
	s_nop 1
	v_writelane_b32 v252, s1, 54
	s_add_u32 s0, s68, 0x4d00
	s_addc_u32 s1, s69, 0
	s_add_u32 s82, s68, 0x4e00
	v_writelane_b32 v252, s0, 55
	s_addc_u32 s83, s69, 0
	s_nop 0
	v_writelane_b32 v252, s1, 56
	s_add_u32 s0, s68, 0x4f00
	s_addc_u32 s1, s69, 0
	s_add_u32 s72, s68, 0x5000
	s_addc_u32 s73, s69, 0
	s_add_u32 s74, s68, 0x5100
	s_addc_u32 s75, s69, 0
	s_add_u32 s76, s68, 0x5200
	s_addc_u32 s77, s69, 0
	s_add_u32 s78, s68, 0x5300
	s_addc_u32 s79, s69, 0
	s_cmp_eq_u32 s3, 15
	s_cselect_b64 s[22:23], -1, 0
	v_writelane_b32 v252, s22, 57
	s_cmp_eq_u32 s3, 14
	s_nop 0
	v_writelane_b32 v252, s23, 58
	s_cselect_b64 s[22:23], -1, 0
	v_writelane_b32 v252, s22, 59
	s_cmp_eq_u32 s3, 13
	s_nop 0
	v_writelane_b32 v252, s23, 60
	s_cselect_b64 s[22:23], -1, 0
	v_writelane_b32 v252, s22, 61
	s_cmp_eq_u32 s3, 12
	s_nop 0
	v_writelane_b32 v252, s23, 62
	s_cselect_b64 s[22:23], -1, 0
	v_writelane_b32 v252, s22, 63
	s_cmp_eq_u32 s3, 11
	s_nop 0
	v_writelane_b32 v253, s23, 0
	s_cselect_b64 s[22:23], -1, 0
	v_writelane_b32 v253, s22, 1
	s_cmp_eq_u32 s3, 10
	s_nop 0
	v_writelane_b32 v253, s23, 2
	s_cselect_b64 s[22:23], -1, 0
	v_writelane_b32 v253, s22, 3
	s_cmp_eq_u32 s3, 9
	s_nop 0
	v_writelane_b32 v253, s23, 4
	s_cselect_b64 s[22:23], -1, 0
	v_writelane_b32 v253, s22, 5
	s_cmp_eq_u32 s3, 8
	s_nop 0
	v_writelane_b32 v253, s23, 6
	s_cselect_b64 s[22:23], -1, 0
	v_writelane_b32 v253, s22, 7
	s_cmp_eq_u32 s3, 7
	s_nop 0
	v_writelane_b32 v253, s23, 8
	s_cselect_b64 s[22:23], -1, 0
	v_writelane_b32 v253, s22, 9
	s_cmp_eq_u32 s3, 6
	s_nop 0
	v_writelane_b32 v253, s23, 10
	s_cselect_b64 s[22:23], -1, 0
	v_writelane_b32 v253, s22, 11
	s_cmp_eq_u32 s3, 5
	s_nop 0
	v_writelane_b32 v253, s23, 12
	s_cselect_b64 s[22:23], -1, 0
	v_writelane_b32 v253, s22, 13
	s_cmp_eq_u32 s3, 4
	s_nop 0
	v_writelane_b32 v253, s23, 14
	s_cselect_b64 s[22:23], -1, 0
	v_writelane_b32 v253, s22, 15
	s_cmp_eq_u32 s3, 3
	s_nop 0
	v_writelane_b32 v253, s23, 16
	s_cselect_b64 s[22:23], -1, 0
	v_writelane_b32 v253, s22, 17
	s_cmp_eq_u32 s3, 2
	s_nop 0
	v_writelane_b32 v253, s23, 18
	s_cselect_b64 s[22:23], -1, 0
	v_writelane_b32 v253, s22, 19
	s_cmp_eq_u32 s3, 1
	s_nop 0
	v_writelane_b32 v253, s23, 20
	s_cselect_b64 s[22:23], -1, 0
	v_writelane_b32 v253, s22, 21
	s_cmp_eq_u32 s3, 0
	s_nop 0
	v_writelane_b32 v253, s23, 22
	s_cselect_b64 s[22:23], -1, 0
	s_lshl_b32 s3, s17, 2
	s_add_u32 s3, s14, s3
	v_writelane_b32 v253, s22, 23
	s_addc_u32 s14, s15, 0
	s_nop 0
;     __host__ __device__ bool next(int i, Unit& u) const {
;         const long L = (long)i * G + c; if (L >= nwg) return false;
;         int wgid = (int)L; { const int q = nwg / NXCD, r = nwg % NXCD, xcd = wgid % NXCD, off = wgid / NXCD; wgid = (xcd < r ? xcd * (q + 1) : r * (q + 1) + (xcd - r) * q) + off; }
;         const int nig = WGM * nN, gid = wgid / nig, fm = gid * WGM, gsz = (nM - fm) < WGM ? (nM - fm) : WGM;
;         u.pm = fm + ((wgid % nig) % gsz); u.pn = (wgid % nig) / gsz; return true;
; __global__ void __launch_bounds__(NTHR, 2) fwd_megakernel(Args args) {
;     ...
;             const abf* Qb = (const abf*)Z + 3 * CWD; const abf* Kb = (const abf*)Z + 4 * CWD;
;             constexpr int NQB = S / att::QB, NITEM = NH * (NQB / 2);
;             unsigned ord = 0u;
;             {   float ce[NH];
; #pragma unroll
;                 for (int h = 0; h < NH; ++h) ce[h] = cs[(size_t)h * S + S - 1];
	v_writelane_b32 v253, s23, 24
	s_add_u32 s22, s3, 0x1400
	s_addc_u32 s23, s14, 0
	v_writelane_b32 v253, s22, 25
	s_nop 1
	v_writelane_b32 v253, s23, 26
	s_add_u32 s22, s3, 0x2400
	s_addc_u32 s23, s14, 0
	v_writelane_b32 v253, s22, 27
	s_add_u32 s14, s68, 0x7400
	s_addc_u32 s15, s69, 0
	v_writelane_b32 v253, s23, 28
	v_writelane_b32 v253, s14, 29
	s_nop 1
	v_writelane_b32 v253, s15, 30
	s_add_u32 s14, s68, 0x7500
	s_addc_u32 s15, s69, 0
	v_writelane_b32 v253, s14, 31
	s_cmp_lt_i32 s2, 8
	s_nop 0
	v_writelane_b32 v253, s15, 32
	s_cselect_b64 s[14:15], -1, 0
	v_writelane_b32 v253, s14, 33
	s_ashr_i32 s3, s2, 31
	s_nop 0
	v_writelane_b32 v253, s15, 34
	s_lshl_b64 s[14:15], s[2:3], 2
	s_add_u32 s14, s18, s14
	v_writelane_b32 v253, s18, 35
	s_addc_u32 s15, s19, s15
	s_nop 0
	v_writelane_b32 v253, s19, 36
	v_writelane_b32 v253, s14, 37
	s_nop 1
	v_writelane_b32 v253, s15, 38
	s_lshl_b64 s[14:15], s[2:3], 16
	v_writelane_b32 v253, s20, 39
	s_add_u32 s14, s20, s14
	v_writelane_b32 v253, s21, 40
	s_addc_u32 s15, s21, s15
	v_writelane_b32 v253, s14, 41
	s_cmpk_lt_i32 s2, 0xa00
	s_nop 0
	v_writelane_b32 v253, s15, 42
	s_cselect_b64 s[14:15], -1, 0
	v_writelane_b32 v253, s14, 43
	s_ashr_i32 s33, s70, 31
	s_nop 0
	v_writelane_b32 v253, s15, 44
	s_lshr_b32 s14, s3, 29
	s_add_i32 s14, s2, s14
	s_ashr_i32 s15, s14, 3
	s_and_b32 s14, s14, -8
	s_sub_i32 s14, s2, s14
	s_add_u32 s17, s68, 0x8001800
	v_writelane_b32 v253, s17, 45
	s_addc_u32 s17, s69, 0
	v_writelane_b32 v253, s17, 46
	s_add_u32 s17, s68, 0x8002000
	v_writelane_b32 v253, s17, 47
	s_addc_u32 s17, s69, 0
	v_writelane_b32 v253, s17, 48
	s_add_u32 s17, s68, 0x8000
	v_writelane_b32 v253, s17, 49
	s_addc_u32 s17, s69, 0
	v_writelane_b32 v253, s17, 50
	s_ashr_i32 s17, s70, 3
	s_mul_i32 s17, s17, s14
	s_add_i32 s17, s17, s15
	s_and_b32 s18, s70, 7
	s_add_u32 s20, s68, 0x8003000
	s_addc_u32 s21, s69, 0
	v_writelane_b32 v253, s20, 51
	s_cmpk_lt_i32 s2, 0x200
	s_nop 0
	v_writelane_b32 v253, s21, 52
	s_cselect_b64 s[20:21], -1, 0
	v_writelane_b32 v253, s20, 53
	s_lshl_b32 s19, s14, 6
	s_nop 0
	v_writelane_b32 v253, s21, 54
	s_add_u32 s20, s68, 0x8004000
	s_addc_u32 s21, s69, 0
	v_writelane_b32 v253, s20, 55
	s_cmpk_lt_i32 s2, 0x800
	s_nop 0
	v_writelane_b32 v253, s21, 56
	s_cselect_b64 s[20:21], -1, 0
	v_writelane_b32 v253, s20, 57
	s_nop 1
	v_writelane_b32 v253, s21, 58
	s_lshl_b32 s20, s14, 8
	s_cmp_lt_i32 s14, 0
	s_mul_i32 s21, s14, 0x41
	s_cselect_b32 s19, s21, s19
	s_movk_i32 s21, 0x141
	s_cselect_b32 s21, s21, 0x140
	s_mul_i32 s21, s14, s21
	s_mulk_i32 s14, 0x101
	s_cselect_b32 s22, s14, s20
	s_add_i32 s21, s21, s15
	s_mul_hi_i32 s14, s21, 0x66666667
	s_lshr_b32 s20, s14, 31
	s_ashr_i32 s14, s14, 7
	s_add_i32 s14, s14, s20
	s_mul_i32 s20, s14, 0x140
	s_sub_i32 s20, s21, s20
	s_lshr_b32 s21, s20, 3
	s_lshl_b32 s21, s21, 1
	s_mov_b32 s23, s21
	s_add_i32 s21, s21, 48
	s_cmpk_ge_i32 s21, 0x50
	s_cselect_b32 s23, 0x50, 0
	s_sub_i32 s21, s21, s23
	s_and_b32 s20, s20, 7
	s_lshl_b32 s14, s14, 3
	s_add_i32 s44, s14, s20
	s_ashr_i32 s14, s21, 1
	v_writelane_b32 v253, s14, 59
	s_lshr_b32 s14, s21, 1
	s_add_u32 s20, s68, 0x18fffc
	s_addc_u32 s21, s69, 0
	v_writelane_b32 v253, s20, 60
	s_nop 1
	v_writelane_b32 v253, s21, 61
	s_add_u32 s20, s68, 0x19fffc
	s_addc_u32 s21, s69, 0
	v_writelane_b32 v253, s20, 62
	s_nop 1
	v_writelane_b32 v253, s21, 63
	s_add_u32 s20, s68, 0x1afffc
	s_addc_u32 s21, s69, 0
	v_writelane_b32 v254, s20, 0
	s_nop 1
	v_writelane_b32 v254, s21, 1
	s_add_u32 s20, s68, 0x1bfffc
	s_addc_u32 s21, s69, 0
	v_writelane_b32 v254, s20, 2
	s_nop 1
	v_writelane_b32 v254, s21, 3
	s_add_u32 s20, s68, 0x1cfffc
	s_addc_u32 s21, s69, 0
	v_writelane_b32 v254, s20, 4
	s_nop 1
	v_writelane_b32 v254, s21, 5
	s_add_u32 s20, s68, 0x1dfffc
	s_addc_u32 s21, s69, 0
	v_writelane_b32 v254, s20, 6
	s_nop 1
	v_writelane_b32 v254, s21, 7
	s_add_u32 s20, s68, 0x1efffc
	s_addc_u32 s21, s69, 0
	v_writelane_b32 v254, s20, 8
	s_nop 1
	v_writelane_b32 v254, s21, 9
	s_add_u32 s20, s68, 0x1ffffc
	s_addc_u32 s21, s69, 0
	v_writelane_b32 v254, s20, 10
	s_cmp_eq_u32 s18, 0
	s_cselect_b32 s17, s17, s2
	v_writelane_b32 v254, s21, 11
	v_writelane_b32 v254, s17, 12
	s_add_i32 s17, s19, s15
	s_ashr_i32 s18, s17, 31
	s_lshr_b32 s18, s18, 28
	s_add_i32 s18, s17, s18
	s_and_b32 s19, s18, 0xfff0
	s_sub_i32 s17, s17, s19
	s_bfe_u32 s19, s17, 0x10007
	s_add_i32 s19, s17, s19
	s_and_b32 s20, s19, 0xfe
	s_sub_i32 s17, s17, s20
	s_ashr_i32 s18, s18, 4
	s_bfe_i32 s19, s19, 0x80000
	s_lshl_b32 s18, s18, 1
	s_sext_i32_i16 s19, s19
	s_sext_i32_i8 s17, s17
	s_add_i32 s46, s18, s17
	s_lshr_b32 s18, s19, 1
	s_ashr_i32 s47, s46, 31
	s_bfe_i64 s[40:41], s[18:19], 0x100000
	s_ashr_i32 s17, s19, 1
	s_lshl_b64 s[18:19], s[46:47], 19
	s_lshl_b64 s[20:21], s[40:41], 19
	v_writelane_b32 v254, s17, 13
	s_add_u32 s48, s28, s20
	v_writelane_b32 v254, s28, 14
	s_addc_u32 s49, s29, s21
	s_mov_b64 s[68:69], 0x80
	v_writelane_b32 v254, s29, 15
	s_add_u32 s28, s48, 0x40000
	s_addc_u32 s29, s49, 0
	v_writelane_b32 v254, s28, 16
	s_nop 1
	v_writelane_b32 v254, s29, 17
	s_add_u32 s28, s8, s18
	s_addc_u32 s29, s9, s19
	s_add_u32 s50, s28, 0x40000
	v_writelane_b32 v254, s28, 18
	s_addc_u32 s51, s29, 0
	s_nop 0
	v_writelane_b32 v254, s29, 19
	v_writelane_b32 v254, s50, 20
	s_add_u32 s28, s48, 0x40080
	s_nop 0
	v_writelane_b32 v254, s51, 21
	v_writelane_b32 v254, s48, 22
	s_addc_u32 s29, s49, 0
	s_add_u32 s20, s30, s20
	v_writelane_b32 v254, s49, 23
	v_writelane_b32 v254, s28, 24
	s_nop 1
	v_writelane_b32 v254, s29, 25
	v_writelane_b32 v254, s30, 26
	s_addc_u32 s21, s31, s21
	s_add_u32 s28, s20, 0x40000
	v_writelane_b32 v254, s31, 27
	s_addc_u32 s29, s21, 0
; #define PG8_WAIT_V(n) asm volatile("s_waitcnt vmcnt(" #n ")" ::: "memory")
; #define PG8_BAR __builtin_amdgcn_s_barrier()
;     __host__ __device__ bool next(int i, Unit& u) const {
;     ...
;         int wgid = (int)L; { const int q = nwg / NXCD, r = nwg % NXCD, xcd = wgid % NXCD, off = wgid / NXCD; wgid = (xcd < r ? xcd * (q + 1) : r * (q + 1) + (xcd - r) * q) + off; }
;         const int nig = WGM * nN, gid = wgid / nig, fm = gid * WGM, gsz = (nM - fm) < WGM ? (nM - fm) : WGM;
;         u.pm = fm + ((wgid % nig) % gsz); u.pn = (wgid % nig) / gsz; return true;
; template <class Epi, class Sched, bool ALIGN_EPI = false, bool SP2 = false>
; __device__ __forceinline__ void gemm_phase(PG8_LAS unsigned char* lds, const Gemm g, const Sched& S, const Epi& E) {
;     ...
;     const char* cA = (const char*)g.A + (size_t)cur.pm * tstepA; const char* cB = (const char*)g.Bt + (size_t)cur.pn * tstepB;
;     S.a_ready(cur);
;     if constexpr (SP2) {
;         PG8_STAGE(PG8_SB(0, 0), cB, voffB); PG8_STAGE(PG8_SB(0, 1), cB + hstepB, voffB); PG8_STAGE(PG8_SA(0, 0), cA, voffA); PG8_STAGE(PG8_SA(0, 1), cA + hstepA, voffA);
;         if (wr == 1) PG8_BAR;
;         PG8_WAIT_V(2); PG8_BAR;
;         PG8_STAGE(PG8_SB(1, 0), cB + kstep, voffB); PG8_STAGE(PG8_SA(1, 0), cA + kstep, voffA); PG8_STAGE(PG8_SB(1, 1), cB + hstepB + kstep, voffB);
;         PG8_WAIT_V(6); PG8_BAR;
;     } else {
;         PG8_STAGE(PG8_SB(0, 0), cB, voffB); PG8_STAGE(PG8_SA(0, 0), cA, voffA); PG8_STAGE(PG8_SB(0, 1), cB + hstepB, voffB); PG8_STAGE(PG8_SA(0, 1), cA + hstepA, voffA);
;         if (wr == 1) PG8_BAR;
;         PG8_WAIT_V(4); PG8_BAR;
;         PG8_STAGE(PG8_SB(1, 0), cB + kstep, voffB); PG8_STAGE(PG8_SA(1, 0), cA + kstep, voffA); PG8_STAGE(PG8_SB(1, 1), cB + hstepB + kstep, voffB);
;         PG8_WAIT_V(6); PG8_BAR;
;     }
;     for (;;) {
;         const bool has_next = S.next(ui + 1, nxt);
;         const char* nA = has_next ? (const char*)g.A + (size_t)nxt.pm * tstepA : cA; const char* nB = has_next ? (const char*)g.Bt + (size_t)nxt.pn * tstepB : cB;
;         for (int t = 0; t < nt; t += 2) {
;             const bool last = (t == nt - 2);
;             const char* a1 = cA + (size_t)(t + 1) * kstep;
;             const char* a2 = last ? nA : cA + (size_t)(t + 2) * kstep; const char* b2 = last ? nB : cB + (size_t)(t + 2) * kstep;
;             const char* a3 = a2 + kstep; const char* b3 = b2 + kstep;
	v_writelane_b32 v254, s28, 28
	s_add_u32 s18, s42, s18
	s_addc_u32 s19, s43, s19
	v_writelane_b32 v254, s29, 29
	v_writelane_b32 v254, s42, 30
	v_writelane_b32 v254, s43, 31
	s_add_u32 s28, s18, 0x40000
	v_writelane_b32 v254, s18, 32
	s_addc_u32 s29, s19, 0
	s_nop 0
	v_writelane_b32 v254, s19, 33
	v_writelane_b32 v254, s28, 34
	s_add_u32 s18, s20, 0x40080
	s_nop 0
	v_writelane_b32 v254, s29, 35
	v_writelane_b32 v254, s20, 36
	s_addc_u32 s19, s21, 0
	s_add_i32 s15, s22, s15
	s_ashr_i32 s17, s15, 31
	v_writelane_b32 v254, s21, 37
	s_lshr_b32 s17, s17, 24
	v_writelane_b32 v254, s18, 38
	s_add_i32 s17, s15, s17
	s_mov_b32 s28, s87
	v_writelane_b32 v254, s19, 39
	s_and_b32 s18, s17, 0xff00
	s_sub_i32 s15, s15, s18
	s_lshr_b32 s18, s15, 3
	s_lshl_b32 s18, s18, 1
	s_mov_b32 s19, s18
	s_and_b32 s15, s15, 7
	s_ashr_i32 s17, s17, 8
	s_nop 0
	s_lshl_b32 s17, s17, 3
	s_nop 0
	s_nop 0
	s_add_i32 s22, s17, s15
	s_ashr_i32 s15, s18, 1
	v_writelane_b32 v254, s15, 40
	s_lshr_b32 s18, s18, 1
	s_mov_b32 s20, s22
	s_ashr_i32 s23, s22, 31
	s_bfe_i64 s[18:19], s[18:19], 0x100000
	v_writelane_b32 v254, s20, 41
	s_lshl_b64 s[18:19], s[18:19], 20
	s_nop 0
	v_writelane_b32 v254, s21, 42
	s_lshl_b64 s[20:21], s[22:23], 20
	s_add_u32 s18, s36, s18
	s_addc_u32 s19, s37, s19
	s_add_u32 s22, s18, 0x80000
	s_addc_u32 s23, s19, 0
	v_writelane_b32 v254, s22, 43
	s_add_u32 s20, s10, s20
	s_addc_u32 s21, s11, s21
	v_writelane_b32 v254, s23, 44
	s_add_u32 s22, s20, 0x80000
	v_writelane_b32 v254, s20, 45
	s_addc_u32 s23, s21, 0
	s_nop 0
	v_writelane_b32 v254, s21, 46
	v_writelane_b32 v254, s22, 47
	s_add_u32 s20, s18, 0x80080
	s_nop 0
	v_writelane_b32 v254, s23, 48
	v_writelane_b32 v254, s18, 49
	s_addc_u32 s21, s19, 0
	s_nop 0
	v_writelane_b32 v254, s19, 50
	v_writelane_b32 v254, s20, 51
	s_lshl_b64 s[18:19], s[46:47], 22
	s_nop 0
	v_writelane_b32 v254, s21, 52
	s_lshl_b64 s[20:21], s[40:41], 22
	s_add_u32 s20, s38, s20
	v_writelane_b32 v254, s38, 53
	s_addc_u32 s21, s39, s21
	s_add_u32 s22, s20, 0x200000
	v_writelane_b32 v254, s39, 54
	s_addc_u32 s23, s21, 0
	v_writelane_b32 v254, s22, 55
	s_add_u32 s18, s4, s18
	s_addc_u32 s19, s5, s19
	v_writelane_b32 v254, s23, 56
	s_add_u32 s22, s18, 0x200000
	v_writelane_b32 v254, s18, 57
	s_addc_u32 s23, s19, 0
	s_movk_i32 s39, 0xbfff
	v_writelane_b32 v254, s19, 58
	v_writelane_b32 v254, s22, 59
	s_add_u32 s18, s20, 0x200080
	s_nop 0
	v_writelane_b32 v254, s23, 60
	v_writelane_b32 v254, s20, 61
	s_addc_u32 s19, s21, 0
	s_ashr_i32 s45, s44, 31
	v_writelane_b32 v254, s21, 62
	v_writelane_b32 v254, s18, 63
	s_bfe_i64 s[14:15], s[14:15], 0x100000
	s_lshl_b64 s[14:15], s[14:15], 20
	v_writelane_b32 v255, s19, 0
	s_mov_b32 s18, s44
	v_writelane_b32 v255, s18, 1
	s_nop 1
	v_writelane_b32 v255, s19, 2
	s_lshl_b64 s[18:19], s[44:45], 20
	s_add_u32 s14, s26, s14
	v_writelane_b32 v255, s26, 3
	s_addc_u32 s15, s27, s15
	s_add_u32 s20, s14, 0x80000
	v_writelane_b32 v255, s27, 4
	s_addc_u32 s21, s15, 0
	v_writelane_b32 v255, s20, 5
	s_add_u32 s18, s6, s18
	s_addc_u32 s19, s7, s19
	v_writelane_b32 v255, s21, 6
	s_add_u32 s20, s18, 0x80000
	v_writelane_b32 v255, s18, 7
	s_addc_u32 s21, s19, 0
	s_nop 0
	v_writelane_b32 v255, s19, 8
	v_writelane_b32 v255, s20, 9
	s_add_u32 s18, s14, 0x80080
	s_nop 0
	v_writelane_b32 v255, s21, 10
	v_writelane_b32 v255, s14, 11
	s_addc_u32 s19, s15, 0
	s_nop 0
	v_writelane_b32 v255, s15, 12
	v_writelane_b32 v255, s18, 13
	s_lshl_b64 s[14:15], s[40:41], 20
	s_nop 0
	v_writelane_b32 v255, s19, 14
	s_mov_b32 s18, s46
	v_writelane_b32 v255, s18, 15
	s_nop 1
	v_writelane_b32 v255, s19, 16
	s_lshl_b64 s[18:19], s[46:47], 20
	s_add_u32 s20, s34, s14
	v_writelane_b32 v255, s34, 17
	s_addc_u32 s21, s35, s15
	s_add_u32 s14, s20, 0x80000
	v_writelane_b32 v255, s35, 18
	s_addc_u32 s15, s21, 0
	v_writelane_b32 v255, s14, 19
	s_add_u32 s18, s6, s18
	s_addc_u32 s19, s7, s19
	v_writelane_b32 v255, s15, 20
	s_movk_i32 s14, 0x3ff
	v_and_or_b32 v0, v0, s14, v202
	s_add_u32 s14, s18, 0x80000
	v_writelane_b32 v255, s18, 21
	s_addc_u32 s15, s19, 0
	s_mov_b64 s[34:35], 0x2000
	v_writelane_b32 v255, s19, 22
	v_writelane_b32 v255, s14, 23
	s_nop 1
	v_writelane_b32 v255, s15, 24
	s_add_u32 s14, s20, 0x80080
	v_writelane_b32 v255, s20, 25
	s_addc_u32 s15, s21, 0
	s_nop 0
	v_writelane_b32 v255, s21, 26
	v_writelane_b32 v255, s14, 27
	s_nop 1
	v_writelane_b32 v255, s15, 28
	s_abs_i32 s14, s70
	s_sub_i32 s15, 1, s14
	s_cmp_lt_u32 s14, 2
	s_cselect_b32 s15, s15, 1
	s_sub_i32 s16, s15, s14
	s_cmp_ge_u32 s15, s14
	s_cselect_b32 s14, s16, s15
	s_cmp_eq_u32 s2, s14
	s_cselect_b64 s[14:15], -1, 0
	v_writelane_b32 v255, s14, 29
	s_lshl_b32 s22, s70, 10
	s_add_i32 s38, 0, 0x20808
	v_writelane_b32 v255, s15, 30
	s_lshl_b32 s14, s2, 8
	s_lshl_b32 s15, s97, 5
	s_add_i32 s14, s14, s15
	v_writelane_b32 v255, s14, 31
	s_lshl_b32 s14, s2, 10
	v_writelane_b32 v255, s14, 32
	s_lshl_b32 s14, s70, 8
	v_writelane_b32 v255, s14, 33
	s_add_i32 s14, s24, 0xa800
	v_writelane_b32 v255, s14, 34
	s_add_i32 s14, s24, 0xc800
	v_writelane_b32 v255, s14, 35
	s_add_i32 s14, s24, 0xd000
	v_writelane_b32 v255, s14, 36
	s_add_i32 s14, s24, 0xd400
	v_writelane_b32 v255, s14, 37
	s_mov_b32 s14, s24
	v_writelane_b32 v255, s14, 38
	s_nop 1
	v_writelane_b32 v255, s15, 39
	s_add_i32 s14, s24, 0xd800
	v_writelane_b32 v255, s14, 40
	s_add_i32 s14, 0, 0x20840
	v_writelane_b32 v255, s14, 41
	s_add_i32 s14, 0, 0x20844
	v_writelane_b32 v255, s14, 42
	s_add_i32 s14, 0, 0x20800
	v_writelane_b32 v255, s14, 43
	s_add_i32 s14, 0, 0x2080c
	v_writelane_b32 v255, s14, 44
	s_add_i32 s14, 0, 0x20804
	v_writelane_b32 v255, s14, 45
	v_cmp_eq_u32_e64 s[14:15], 0, v0
	s_nop 1
	v_writelane_b32 v255, s14, 46
	s_nop 1
	v_writelane_b32 v255, s15, 47
	v_writelane_b32 v255, s56, 48
	s_mov_b64 s[14:15], -1
	s_nop 0
	v_writelane_b32 v255, s57, 49
	v_writelane_b32 v255, s97, 50
	v_writelane_b32 v255, s36, 51
	s_nop 1
	v_writelane_b32 v255, s37, 52
	v_writelane_b32 v255, s22, 53
	s_branch .LBB0_8

;     __host__ __device__ bool next(int i, Unit& u) const {
;         const long L = (long)i * G + c; if (L >= nwg) return false;
;         int wgid = (int)L; { const int q = nwg / NXCD, r = nwg % NXCD, xcd = wgid % NXCD, off = wgid / NXCD; wgid = (xcd < r ? xcd * (q + 1) : r * (q + 1) + (xcd - r) * q) + off; }
;         const int nig = WGM * nN, gid = wgid / nig, fm = gid * WGM, gsz = (nM - fm) < WGM ? (nM - fm) : WGM;
;         u.pm = fm + ((wgid % nig) % gsz); u.pn = (wgid % nig) / gsz; return true;
.LBB0_153:
	s_add_i32 s97, s97, 1
	s_mul_i32 s15, s97, s33
	s_mul_hi_u32 s24, s97, s70
	s_add_i32 s24, s24, s15
	s_mul_i32 s15, s97, s70
	s_add_u32 s54, s15, s2
	s_addc_u32 s55, s24, s3
	v_mov_b64_e32 v[0:1], 0xa00
	v_cmp_lt_i64_e64 s[42:43], s[54:55], v[0:1]
	v_mov_b64_e32 v[0:1], 0x9ff
	v_cmp_gt_i64_e32 vcc, s[54:55], v[0:1]
	s_cbranch_vccnz .LBB0_155
	s_ashr_i32 s14, s54, 31
	s_lshr_b32 s14, s14, 29
	s_add_i32 s14, s54, s14
	s_ashr_i32 s15, s14, 3
	s_and_b32 s14, s14, -8
	s_sub_i32 s14, s54, s14
	s_cmp_lt_i32 s14, 0
	s_movk_i32 s24, 0x141
	s_cselect_b32 s24, s24, 0x140
	s_mul_i32 s14, s14, s24
	s_add_i32 s14, s14, s15
	s_mul_hi_i32 s15, s14, 0x66666667
	s_lshr_b32 s24, s15, 31
	s_ashr_i32 s15, s15, 7
	s_add_i32 s15, s15, s24
	s_lshl_b32 s24, s15, 3
	s_sub_i32 s25, 64, s24
	s_min_i32 s25, s25, 8
	s_abs_i32 s26, s25
	v_cvt_f32_u32_e32 v0, s26
	s_sub_i32 s28, 0, s26
	s_mulk_i32 s15, 0x140
	s_sub_i32 s14, s14, s15
	v_rcp_iflag_f32_e32 v0, v0
	s_abs_i32 s15, s14
	s_xor_b32 s27, s14, s25
	s_ashr_i32 s27, s27, 31
	v_mul_f32_e32 v0, 0x4f7ffffe, v0
	v_cvt_u32_f32_e32 v0, v0
	s_nop 0
	v_readfirstlane_b32 s29, v0
	s_mul_i32 s28, s28, s29
	s_mul_hi_u32 s28, s29, s28
	s_add_i32 s29, s29, s28
	s_mul_hi_u32 s28, s15, s29
	s_mul_i32 s29, s28, s26
	s_sub_i32 s15, s15, s29
	s_add_i32 s30, s28, 1
	s_sub_i32 s29, s15, s26
	s_cmp_ge_u32 s15, s26
	s_cselect_b32 s28, s30, s28
	s_cselect_b32 s15, s29, s15
	s_add_i32 s29, s28, 1
	s_cmp_ge_u32 s15, s26
	s_cselect_b32 s15, s29, s28
	s_xor_b32 s15, s15, s27
	s_sub_i32 s62, s15, s27
	s_mul_i32 s15, s62, s25
	s_sub_i32 s14, s14, s15
	s_add_i32 s14, s24, s14
	s_add_i32 s62, s62, 24
	s_cmpk_ge_i32 s62, 0x28
	s_cselect_b32 s15, 40, 0
	s_sub_i32 s62, s62, s15
